# SSM part E: pipelined LDS reads (8-deep) for Toeplitz/W_H MFMA chains
# speedup vs baseline: 1.0035x; 1.0035x over previous
; __device__ void phase_ssm(int j, unsigned char* lds) {
;     ...
;             for (int cb = 0; cb < 2; ++cb) {
;                 f32x16 acc;
; #pragma unroll
;                 for (int i = 0; i < 16; ++i) acc[i] = 0.f;
;                 const int ch = cb * 32 + l31;
;                 const unsigned char* ub0 = lds + L_UB + ch * U_PITCH + h * 16; const unsigned char* hb0 = lds + L_SB + ch * (S_PITCH * 4) + h * 16;
; #pragma unroll
;                 for (int g8 = 0; g8 < 2; ++g8) if (8 * g8 <= 2 * mb3 + 1) { bf16x8 B[8];
; #pragma unroll
;                     for (int i = 0; i < 8; ++i) B[i] = *(const bf16x8*)(ub0 + (g8 * 8 + i) * 32);
; #pragma unroll
;                     for (int i = 0; i < 8; ++i) acc = __builtin_amdgcn_mfma_f32_32x32x16_bf16(FT[g8 * 8 + i], B[i], acc, 0, 0, 0); }
;                 { bf16x8 B[8];
; #pragma unroll
;                     for (int i = 0; i < 8; ++i) B[i] = *(const bf16x8*)(hb0 + i * 32);
; #pragma unroll
;                     for (int i = 0; i < 8; ++i) acc = __builtin_amdgcn_mfma_f32_32x32x16_bf16(FH[i], B[i], acc, 0, 0, 0); }
;                 u32x2 uwv[4]; const f32x4 dA = *(const f32x4*)(lds + L_D + 16 * h), dB = *(const f32x4*)(lds + L_D + 32 + 16 * h);
; #pragma unroll
;                 for (int rr = 0; rr < 4; ++rr) uwv[rr] = *(const u32x2*)(lds + L_UB + ch * U_PITCH + (2 * mb3 + (rr >> 1)) * 32 + (8 * (rr & 1) + 4 * h) * 2);
.LBB0_722:
	v_or_b32_e32 v151, s25, v145
	v_mov_b32_e32 v0, s93
	v_mad_u32_u24 v158, v151, s2, v0
	v_mul_u32_u24_e32 v0, 0x210, v151
	v_add_u32_e32 v159, v158, v165
	v_add_u32_e32 v184, v168, v0
	v_lshl_or_b32 v0, v151, 4, s24
	v_add_u32_e32 v204, 0x25c00, v165
	v_add_u32_e32 v205, 0x25c20, v165
	v_add3_u32 v206, v158, s40, v161
	v_add3_u32 v231, v158, s40, v171
	v_lshl_add_u64 v[162:163], v[0:1], 0, s[26:27]
	v_lshl_add_u64 v[134:135], v[0:1], 0, s[10:11]
	v_lshlrev_b64 v[162:163], 5, v[162:163]
	v_lshlrev_b64 v[134:135], 5, v[134:135]
	v_lshl_add_u64 v[162:163], v[156:157], 0, v[162:163]
	v_lshl_add_u64 v[134:135], v[156:157], 0, v[134:135]
	s_and_b64 vcc, exec, s[20:21]
	s_cbranch_vccnz .Lssm_e_long
	ds_read_b128 v[218:221], v159
	ds_read_b128 v[222:225], v159 offset:32
	ds_read_b128 v[188:191], v159 offset:64
	ds_read_b128 v[192:195], v159 offset:96
	ds_read_b128 v[196:199], v159 offset:128
	ds_read_b128 v[200:203], v159 offset:160
	ds_read_b128 v[172:175], v159 offset:192
	ds_read_b128 v[146:149], v159 offset:224
	s_waitcnt lgkmcnt(7)
	v_mfma_f32_32x32x16_bf16 v[2:17], v[34:37], v[218:221], 0
	ds_read_b128 v[218:221], v184
	s_waitcnt lgkmcnt(7)
	v_mfma_f32_32x32x16_bf16 v[2:17], v[38:41], v[222:225], v[2:17]
	ds_read_b128 v[222:225], v184 offset:32
	s_waitcnt lgkmcnt(7)
	v_mfma_f32_32x32x16_bf16 v[2:17], v[42:45], v[188:191], v[2:17]
	ds_read_b128 v[188:191], v184 offset:64
	s_waitcnt lgkmcnt(7)
	v_mfma_f32_32x32x16_bf16 v[2:17], v[46:49], v[192:195], v[2:17]
	ds_read_b128 v[192:195], v184 offset:96
	s_waitcnt lgkmcnt(7)
	v_mfma_f32_32x32x16_bf16 v[2:17], v[50:53], v[196:199], v[2:17]
	ds_read_b128 v[196:199], v184 offset:128
	s_waitcnt lgkmcnt(7)
	v_mfma_f32_32x32x16_bf16 v[2:17], v[54:57], v[200:203], v[2:17]
	ds_read_b128 v[200:203], v184 offset:160
	s_waitcnt lgkmcnt(7)
	v_mfma_f32_32x32x16_bf16 v[2:17], v[58:61], v[172:175], v[2:17]
	ds_read_b128 v[172:175], v184 offset:192
	s_waitcnt lgkmcnt(7)
	v_mfma_f32_32x32x16_bf16 v[2:17], v[62:65], v[146:149], v[2:17]
	ds_read_b128 v[146:149], v184 offset:224
	s_waitcnt lgkmcnt(7)
	v_mfma_f32_32x32x16_bf16 v[2:17], v[98:101], v[218:221], v[2:17]
	ds_read_b128 v[226:229], v204
	s_waitcnt lgkmcnt(7)
	v_mfma_f32_32x32x16_bf16 v[2:17], v[102:105], v[222:225], v[2:17]
	ds_read_b128 v[244:247], v205
	s_waitcnt lgkmcnt(7)
	v_mfma_f32_32x32x16_bf16 v[2:17], v[106:109], v[188:191], v[2:17]
	ds_read2_b64 v[248:251], v206 offset1:4
	s_waitcnt lgkmcnt(7)
	v_mfma_f32_32x32x16_bf16 v[2:17], v[110:113], v[192:195], v[2:17]
	ds_read2_b64 v[184:187], v231 offset1:4
	s_waitcnt lgkmcnt(7)
	v_mfma_f32_32x32x16_bf16 v[2:17], v[114:117], v[196:199], v[2:17]
	s_waitcnt lgkmcnt(6)
	v_mfma_f32_32x32x16_bf16 v[2:17], v[118:121], v[200:203], v[2:17]
	s_waitcnt lgkmcnt(5)
	v_mfma_f32_32x32x16_bf16 v[2:17], v[122:125], v[172:175], v[2:17]
	s_waitcnt lgkmcnt(4)
	v_mfma_f32_32x32x16_bf16 v[2:17], v[126:129], v[146:149], v[2:17]
	s_branch .Lssm_e_epi
.Lssm_e_long:
	ds_read_b128 v[218:221], v159
	ds_read_b128 v[222:225], v159 offset:32
	ds_read_b128 v[188:191], v159 offset:64
	ds_read_b128 v[192:195], v159 offset:96
	ds_read_b128 v[196:199], v159 offset:128
	ds_read_b128 v[200:203], v159 offset:160
	ds_read_b128 v[172:175], v159 offset:192
	ds_read_b128 v[146:149], v159 offset:224
	s_waitcnt lgkmcnt(7)
	v_mfma_f32_32x32x16_bf16 v[2:17], v[34:37], v[218:221], 0
	ds_read_b128 v[218:221], v159 offset:256
	s_waitcnt lgkmcnt(7)
	v_mfma_f32_32x32x16_bf16 v[2:17], v[38:41], v[222:225], v[2:17]
	ds_read_b128 v[222:225], v159 offset:288
	s_waitcnt lgkmcnt(7)
	v_mfma_f32_32x32x16_bf16 v[2:17], v[42:45], v[188:191], v[2:17]
	ds_read_b128 v[188:191], v159 offset:320
	s_waitcnt lgkmcnt(7)
	v_mfma_f32_32x32x16_bf16 v[2:17], v[46:49], v[192:195], v[2:17]
	ds_read_b128 v[192:195], v159 offset:352
	s_waitcnt lgkmcnt(7)
	v_mfma_f32_32x32x16_bf16 v[2:17], v[50:53], v[196:199], v[2:17]
	ds_read_b128 v[196:199], v159 offset:384
	s_waitcnt lgkmcnt(7)
	v_mfma_f32_32x32x16_bf16 v[2:17], v[54:57], v[200:203], v[2:17]
	ds_read_b128 v[200:203], v159 offset:416
	s_waitcnt lgkmcnt(7)
	v_mfma_f32_32x32x16_bf16 v[2:17], v[58:61], v[172:175], v[2:17]
	ds_read_b128 v[172:175], v159 offset:448
	s_waitcnt lgkmcnt(7)
	v_mfma_f32_32x32x16_bf16 v[2:17], v[62:65], v[146:149], v[2:17]
	ds_read_b128 v[146:149], v159 offset:480
	s_waitcnt lgkmcnt(7)
	v_mfma_f32_32x32x16_bf16 v[2:17], v[66:69], v[218:221], v[2:17]
	ds_read_b128 v[218:221], v184
	s_waitcnt lgkmcnt(7)
	v_mfma_f32_32x32x16_bf16 v[2:17], v[70:73], v[222:225], v[2:17]
	ds_read_b128 v[222:225], v184 offset:32
	s_waitcnt lgkmcnt(7)
	v_mfma_f32_32x32x16_bf16 v[2:17], v[74:77], v[188:191], v[2:17]
	ds_read_b128 v[188:191], v184 offset:64
	s_waitcnt lgkmcnt(7)
	v_mfma_f32_32x32x16_bf16 v[2:17], v[78:81], v[192:195], v[2:17]
	ds_read_b128 v[192:195], v184 offset:96
	s_waitcnt lgkmcnt(7)
	v_mfma_f32_32x32x16_bf16 v[2:17], v[82:85], v[196:199], v[2:17]
	ds_read_b128 v[196:199], v184 offset:128
	s_waitcnt lgkmcnt(7)
	v_mfma_f32_32x32x16_bf16 v[2:17], v[86:89], v[200:203], v[2:17]
	ds_read_b128 v[200:203], v184 offset:160
	s_waitcnt lgkmcnt(7)
	v_mfma_f32_32x32x16_bf16 v[2:17], v[90:93], v[172:175], v[2:17]
	ds_read_b128 v[172:175], v184 offset:192
	s_waitcnt lgkmcnt(7)
	v_mfma_f32_32x32x16_bf16 v[2:17], v[94:97], v[146:149], v[2:17]
	ds_read_b128 v[146:149], v184 offset:224
	s_waitcnt lgkmcnt(7)
	v_mfma_f32_32x32x16_bf16 v[2:17], v[98:101], v[218:221], v[2:17]
	ds_read_b128 v[226:229], v204
	s_waitcnt lgkmcnt(7)
	v_mfma_f32_32x32x16_bf16 v[2:17], v[102:105], v[222:225], v[2:17]
	ds_read_b128 v[244:247], v205
	s_waitcnt lgkmcnt(7)
	v_mfma_f32_32x32x16_bf16 v[2:17], v[106:109], v[188:191], v[2:17]
	ds_read2_b64 v[248:251], v206 offset1:4
	s_waitcnt lgkmcnt(7)
	v_mfma_f32_32x32x16_bf16 v[2:17], v[110:113], v[192:195], v[2:17]
	ds_read2_b64 v[184:187], v231 offset1:4
	s_waitcnt lgkmcnt(7)
	v_mfma_f32_32x32x16_bf16 v[2:17], v[114:117], v[196:199], v[2:17]
	s_waitcnt lgkmcnt(6)
	v_mfma_f32_32x32x16_bf16 v[2:17], v[118:121], v[200:203], v[2:17]
	s_waitcnt lgkmcnt(5)
	v_mfma_f32_32x32x16_bf16 v[2:17], v[122:125], v[172:175], v[2:17]
	s_waitcnt lgkmcnt(4)
	v_mfma_f32_32x32x16_bf16 v[2:17], v[126:129], v[146:149], v[2:17]
; __device__ __forceinline__ unsigned cvt_pk_bf16(float lo, float hi) { unsigned r; asm volatile("v_cvt_pk_bf16_f32 %0, %1, %2" : "=v"(r) : "v"(lo), "v"(hi)); return r; }
; __device__ __forceinline__ float bf_lo(unsigned w) { return __uint_as_float(w << 16); }
; __device__ __forceinline__ float bf_hi(unsigned w) { return __uint_as_float(w & 0xffff0000u); }
; __device__ void phase_ssm(int j, unsigned char* lds) {
;     ...
;                 u32x2 uwv[4]; const f32x4 dA = *(const f32x4*)(lds + L_D + 16 * h), dB = *(const f32x4*)(lds + L_D + 32 + 16 * h);
; #pragma unroll
;                 for (int rr = 0; rr < 4; ++rr) uwv[rr] = *(const u32x2*)(lds + L_UB + ch * U_PITCH + (2 * mb3 + (rr >> 1)) * 32 + (8 * (rr & 1) + 4 * h) * 2);
; #pragma unroll
;                 for (int rr = 0; rr < 4; ++rr) { const int jj = 2 * mb3 + (rr >> 1), p0 = 8 * (rr & 1) + 4 * h;
;                     const u32x2 uw = uwv[rr]; const f32x4 d4 = (rr & 1) ? dB : dA;
;                     const float y0 = acc[4 * rr] + d4[0] * bf_lo(uw.x), y1 = acc[4 * rr + 1] + d4[1] * bf_hi(uw.x);
;                     const float y2 = acc[4 * rr + 2] + d4[2] * bf_lo(uw.y), y3 = acc[4 * rr + 3] + d4[3] * bf_hi(uw.y);
;                     u32x2 o; o.x = cvt_pk_bf16(gelu_tanh_f(y0), gelu_tanh_f(y1)); o.y = cvt_pk_bf16(gelu_tanh_f(y2), gelu_tanh_f(y3));
;                     *(u32x2*)(gbase + ((size_t)seg * (SEGC * TCH) + ch * TCH + jj) * 16 + p0) = o; }
;             }
.Lssm_e_epi:
	s_xor_b64 s[0:1], s[4:5], -1
	s_mov_b32 s25, 32
	s_mov_b64 s[4:5], 0
	s_waitcnt lgkmcnt(0)
	v_lshlrev_b32_e32 v151, 16, v248
	v_lshlrev_b32_e32 v230, 16, v185
	v_and_b32_e32 v218, 0xffff0000, v248
	v_lshlrev_b32_e32 v219, 16, v249
	v_and_b32_e32 v220, 0xffff0000, v249
	v_lshlrev_b32_e32 v221, 16, v184
	v_and_b32_e32 v184, 0xffff0000, v184
	s_nop 4
	v_fma_f32 v2, v226, v151, v2
	v_fma_f32 v3, v227, v218, v3
	v_fma_f32 v4, v228, v219, v4
	v_fma_f32 v5, v229, v220, v5
	v_fma_f32 v7, v245, v184, v7
	v_mul_f32_e32 v151, v2, v2
	v_mul_f32_e32 v184, v3, v3
	v_mul_f32_e32 v218, v4, v4
	v_mul_f32_e32 v219, v5, v5
	v_fmamk_f32 v151, v151, 0xbdd2d3e8, v237
	v_fmamk_f32 v184, v184, 0xbdd2d3e8, v237
	v_fmamk_f32 v218, v218, 0xbdd2d3e8, v237
	v_fmamk_f32 v219, v219, 0xbdd2d3e8, v237
	v_mul_f32_e32 v151, v2, v151
	v_mul_f32_e32 v184, v3, v184
	v_fma_f32 v6, v244, v221, v6
	v_mul_f32_e32 v218, v4, v218
	v_mul_f32_e32 v219, v5, v219
	v_exp_f32_e32 v151, v151
	v_exp_f32_e32 v184, v184
	v_mul_f32_e32 v220, v6, v6
	v_exp_f32_e32 v218, v218
	v_exp_f32_e32 v219, v219
	v_fmamk_f32 v220, v220, 0xbdd2d3e8, v237
	v_mul_f32_e32 v220, v6, v220
	v_exp_f32_e32 v220, v220
	v_add_f32_e32 v151, 1.0, v151
	v_add_f32_e32 v184, 1.0, v184
	v_add_f32_e32 v218, 1.0, v218
	v_add_f32_e32 v219, 1.0, v219
	v_rcp_f32_e32 v151, v151
	v_rcp_f32_e32 v184, v184
	v_rcp_f32_e32 v218, v218
	v_rcp_f32_e32 v219, v219
	v_add_f32_e32 v220, 1.0, v220
	v_rcp_f32_e32 v220, v220
	v_mul_f32_e32 v2, v2, v151
	v_mul_f32_e32 v3, v3, v184
	v_mul_f32_e32 v4, v4, v218
	v_mul_f32_e32 v5, v5, v219
	v_cvt_pk_bf16_f32 v2, v2, v3
	v_cvt_pk_bf16_f32 v3, v4, v5
	global_store_dwordx2 v[162:163], v[2:3], off
	v_and_b32_e32 v3, 0xffff0000, v185
	v_mul_f32_e32 v221, v7, v7
	v_fma_f32 v3, v247, v3, v9
	v_fma_f32 v8, v246, v230, v8
	v_fmamk_f32 v221, v221, 0xbdd2d3e8, v237
	v_mul_f32_e32 v4, v6, v220
	v_mul_f32_e32 v6, v3, v3
	v_mul_f32_e32 v221, v7, v221
	v_mul_f32_e32 v5, v8, v8
	v_fmamk_f32 v6, v6, 0xbdd2d3e8, v237
	v_exp_f32_e32 v2, v221
	v_fmamk_f32 v5, v5, 0xbdd2d3e8, v237
	v_mul_f32_e32 v6, v3, v6
	v_mul_f32_e32 v5, v8, v5
	v_exp_f32_e32 v6, v6
	v_exp_f32_e32 v5, v5
	v_add_f32_e32 v2, 1.0, v2
	v_rcp_f32_e32 v2, v2
	v_add_f32_e32 v6, 1.0, v6
	v_add_f32_e32 v5, 1.0, v5
	v_rcp_f32_e32 v6, v6
	v_rcp_f32_e32 v5, v5
	v_mul_f32_e32 v2, v7, v2
	v_cvt_pk_bf16_f32 v2, v4, v2
	v_mul_f32_e32 v3, v3, v6
	v_mul_f32_e32 v4, v8, v5
	v_cvt_pk_bf16_f32 v3, v4, v3
	global_store_dwordx2 v[162:163], v[2:3], off offset:16
	v_lshlrev_b32_e32 v2, 16, v250
	v_fma_f32 v2, v226, v2, v10
	v_mul_f32_e32 v4, v2, v2
	v_fmamk_f32 v4, v4, 0xbdd2d3e8, v237
	v_mul_f32_e32 v4, v2, v4
	v_and_b32_e32 v3, 0xffff0000, v250
	v_exp_f32_e32 v4, v4
	v_fma_f32 v3, v227, v3, v11
	v_mul_f32_e32 v6, v3, v3
	v_fmamk_f32 v6, v6, 0xbdd2d3e8, v237
	v_add_f32_e32 v4, 1.0, v4
	v_mul_f32_e32 v6, v3, v6
	v_rcp_f32_e32 v4, v4
	v_exp_f32_e32 v6, v6
	v_lshlrev_b32_e32 v5, 16, v251
	v_and_b32_e32 v7, 0xffff0000, v251
	v_fma_f32 v5, v228, v5, v12
	v_fma_f32 v7, v229, v7, v13
	v_mul_f32_e32 v2, v2, v4
	v_add_f32_e32 v4, 1.0, v6
	v_mul_f32_e32 v6, v5, v5
	v_mul_f32_e32 v8, v7, v7
	v_fmamk_f32 v6, v6, 0xbdd2d3e8, v237
	v_fmamk_f32 v8, v8, 0xbdd2d3e8, v237
	v_mul_f32_e32 v6, v5, v6
	v_mul_f32_e32 v8, v7, v8
	v_exp_f32_e32 v6, v6
	v_exp_f32_e32 v8, v8
	v_rcp_f32_e32 v4, v4
	v_add_f32_e32 v6, 1.0, v6
	v_add_f32_e32 v8, 1.0, v8
	v_rcp_f32_e32 v6, v6
	v_rcp_f32_e32 v8, v8
	v_mul_f32_e32 v3, v3, v4
	v_cvt_pk_bf16_f32 v2, v2, v3
	v_mul_f32_e32 v3, v5, v6
	v_mul_f32_e32 v4, v7, v8
	v_cvt_pk_bf16_f32 v3, v3, v4
	v_lshlrev_b32_e32 v0, 16, v186
	v_fma_f32 v0, v244, v0, v14
	global_store_dwordx2 v[134:135], v[2:3], off
	v_mul_f32_e32 v3, v0, v0
	v_fmamk_f32 v3, v3, 0xbdd2d3e8, v237
	v_mul_f32_e32 v3, v0, v3
	v_and_b32_e32 v2, 0xffff0000, v186
	v_exp_f32_e32 v3, v3
	v_fma_f32 v2, v245, v2, v15
	v_mul_f32_e32 v7, v2, v2
	v_fmamk_f32 v7, v7, 0xbdd2d3e8, v237
	v_add_f32_e32 v3, 1.0, v3
	v_mul_f32_e32 v7, v2, v7
	v_rcp_f32_e32 v3, v3
	v_exp_f32_e32 v7, v7
	v_and_b32_e32 v8, 0xffff0000, v187
	v_lshlrev_b32_e32 v6, 16, v187
	v_fmac_f32_e32 v17, v247, v8
	v_fma_f32 v6, v246, v6, v16
	v_mul_f32_e32 v8, v17, v17
	v_mul_f32_e32 v0, v0, v3
	v_add_f32_e32 v3, 1.0, v7
	v_mul_f32_e32 v7, v6, v6
	v_fmamk_f32 v8, v8, 0xbdd2d3e8, v237
	v_fmamk_f32 v7, v7, 0xbdd2d3e8, v237
	v_mul_f32_e32 v8, v17, v8
	v_mul_f32_e32 v7, v6, v7
	v_exp_f32_e32 v8, v8
	v_exp_f32_e32 v7, v7
	v_rcp_f32_e32 v3, v3
	v_add_f32_e32 v8, 1.0, v8
	v_add_f32_e32 v7, 1.0, v7
	v_rcp_f32_e32 v8, v8
	v_rcp_f32_e32 v7, v7
	v_mul_f32_e32 v2, v2, v3
	v_cvt_pk_bf16_f32 v2, v0, v2
	v_mul_f32_e32 v3, v17, v8
	v_mul_f32_e32 v0, v6, v7
	v_cvt_pk_bf16_f32 v3, v0, v3
	global_store_dwordx2 v[134:135], v[2:3], off offset:16
	s_and_b64 vcc, exec, s[0:1]
	s_cbranch_vccnz .LBB0_716
	s_branch .LBB0_722
